# attention steady loop: K/V LDS-DMA pair issued after the first QK MFMA of each step instead of the eighth (plus barrier invalidate move)
# speedup vs baseline: 1.0018x; 1.0018x over previous
.LBB0_1097:
	v_add_u32_e32 v2, s70, v232
	ds_read_b64_tr_b16 v[182:183], v2 offset:24576
	ds_read_b64_tr_b16 v[184:185], v2 offset:25088
	s_waitcnt lgkmcnt(9)
	v_mfma_f32_32x32x16_bf16 v[82:97], v[174:177], v[130:133], v[82:97]
	v_add_f32_e32 v4, v98, v99
	v_add_f32_e32 v4, v100, v4
	v_add_f32_e32 v4, v101, v4
	v_add_f32_e32 v4, v102, v4
	v_add_f32_e32 v4, v103, v4
	v_cvt_pk_bf16_f32 v142, v98, v99
	v_cvt_pk_bf16_f32 v143, v100, v101
	v_lshl_add_u64 v[240:241], v[188:189], 0, s[62:63]
	s_add_i32 s98, s51, s85
	s_mov_b32 s99, m0
	s_mov_b32 m0, s98
	s_nop 0
	global_load_lds_dwordx4 v[240:241], off
	v_lshl_add_u64 v[242:243], v[186:187], 0, s[62:63]
	s_add_i32 s98, s74, s86
	s_mov_b32 m0, s98
	s_nop 0
	global_load_lds_dwordx4 v[242:243], off
	s_mov_b32 m0, s99
	ds_read_b64_tr_b16 v[178:179], v2 offset:28672
	ds_read_b64_tr_b16 v[180:181], v2 offset:29184
	s_waitcnt lgkmcnt(10)
	v_mfma_f32_32x32x16_bf16 v[50:65], v[166:169], v[130:133], v[50:65]
	v_add_f32_e32 v4, v104, v4
	v_add_f32_e32 v4, v105, v4
	v_add_f32_e32 v4, v106, v4
	v_add_f32_e32 v4, v107, v4
	v_cvt_pk_bf16_f32 v144, v102, v103
	v_cvt_pk_bf16_f32 v145, v104, v105
	ds_read_b64_tr_b16 v[174:175], v2 offset:25600
	ds_read_b64_tr_b16 v[176:177], v2 offset:26112
	s_waitcnt lgkmcnt(11)
	v_mfma_f32_32x32x16_bf16 v[82:97], v[170:173], v[126:129], v[82:97]
	v_add_f32_e32 v4, v108, v4
	v_add_f32_e32 v4, v109, v4
	v_add_f32_e32 v4, v110, v4
	v_add_f32_e32 v4, v111, v4
	v_cvt_pk_bf16_f32 v138, v106, v107
	v_cvt_pk_bf16_f32 v139, v108, v109
	ds_read_b64_tr_b16 v[166:167], v2 offset:29696
	ds_read_b64_tr_b16 v[168:169], v2 offset:30208
	s_waitcnt lgkmcnt(12)
	v_mfma_f32_32x32x16_bf16 v[50:65], v[158:161], v[126:129], v[50:65]
	v_add_f32_e32 v4, v112, v4
	v_add_f32_e32 v4, v113, v4
	v_add_f32_e32 v4, v66, v4
	v_add_f32_e32 v4, v67, v4
	v_cvt_pk_bf16_f32 v140, v110, v111
	v_cvt_pk_bf16_f32 v141, v112, v113
	ds_read_b64_tr_b16 v[158:159], v2 offset:26624
	ds_read_b64_tr_b16 v[160:161], v2 offset:27136
	s_waitcnt lgkmcnt(13)
	v_mfma_f32_32x32x16_bf16 v[82:97], v[162:165], v[118:121], v[82:97]
	v_add_f32_e32 v4, v68, v4
	v_add_f32_e32 v4, v69, v4
	v_add_f32_e32 v4, v70, v4
	v_add_f32_e32 v4, v71, v4
	v_cvt_pk_bf16_f32 v134, v66, v67
	v_cvt_pk_bf16_f32 v135, v68, v69
	ds_read_b64_tr_b16 v[12:13], v2 offset:30720
	ds_read_b64_tr_b16 v[14:15], v2 offset:31232
	s_waitcnt lgkmcnt(14)
	v_mfma_f32_32x32x16_bf16 v[50:65], v[150:153], v[118:121], v[50:65]
	v_add_f32_e32 v4, v72, v4
	v_add_f32_e32 v4, v73, v4
	v_add_f32_e32 v4, v74, v4
	v_add_f32_e32 v4, v75, v4
	v_cvt_pk_bf16_f32 v136, v70, v71
	v_cvt_pk_bf16_f32 v137, v72, v73
	ds_read_b64_tr_b16 v[8:9], v2 offset:27648
	ds_read_b64_tr_b16 v[10:11], v2 offset:28160
	s_waitcnt lgkmcnt(14)
	v_mfma_f32_32x32x16_bf16 v[82:97], v[154:157], v[114:117], v[82:97]
	v_add_f32_e32 v4, v76, v4
	v_add_f32_e32 v4, v77, v4
	v_add_f32_e32 v4, v78, v4
	v_add_f32_e32 v16, v79, v4
	v_cvt_pk_bf16_f32 v122, v74, v75
	v_cvt_pk_bf16_f32 v123, v76, v77
	ds_read_b64_tr_b16 v[4:5], v2 offset:31744
	ds_read_b64_tr_b16 v[6:7], v2 offset:32256
	v_mfma_f32_32x32x16_bf16 v[50:65], v[146:149], v[114:117], v[50:65]
	v_add_f32_e32 v2, v80, v16
	v_add_f32_e32 v2, v81, v2
	v_add_f32_e32 v2, 0, v2
	v_cvt_pk_bf16_f32 v124, v78, v79
	v_cvt_pk_bf16_f32 v125, v80, v81
	s_nop 5
	v_max_f32_e32 v16, v83, v83
	v_max_f32_e32 v17, v82, v82
	v_max_f32_e32 v16, v17, v16
	v_max3_f32 v17, v84, v85, v51
	v_max3_f32 v16, v16, v50, v52
	v_max3_f32 v16, v16, v53, v86
	v_max3_f32 v17, v17, v88, v89
	v_max3_f32 v16, v16, v87, v54
	v_max3_f32 v17, v17, v56, v57
	v_max3_f32 v16, v16, v55, v90
	v_max3_f32 v17, v17, v92, v93
	v_max3_f32 v16, v16, v91, v58
	v_max3_f32 v17, v17, v60, v61
	v_max3_f32 v16, v16, v59, v94
	v_max3_f32 v17, v17, v96, v97
	v_max3_f32 v16, v16, v95, v62
	v_max3_f32 v17, v17, v64, v65
	v_max3_f32 v16, v16, v63, v17
	v_mov_b32_e32 v17, v16
	s_nop 1
	v_permlane32_swap_b32_e32 v16, v17
	v_max_f32_e32 v17, v17, v17
	v_max_f32_e32 v16, v16, v16
	v_max_f32_e32 v16, v16, v17
	v_cmp_lt_f32_e32 vcc, s81, v16
	s_cmp_lg_u64 vcc, 0
	v_add_f32_e32 v2, v233, v2
	s_cselect_b64 s[70:71], -1, 0
	s_cbranch_vccnz .LBB0_1105

.LBB0_1100:
	s_add_i32 s70, s74, 0x2000
	s_cmpk_lg_i32 s74, 0x4000
	s_cselect_b32 s87, s70, 0
	v_add_u32_e32 v6, s51, v232
	ds_read_b64_tr_b16 v[182:183], v6 offset:24576
	ds_read_b64_tr_b16 v[184:185], v6 offset:25088
	s_waitcnt lgkmcnt(9)
	v_mfma_f32_32x32x16_bf16 v[98:113], v[162:165], v[130:133], v[98:113]
	v_add_f32_e32 v4, v82, v83
	v_add_f32_e32 v4, v84, v4
	v_add_f32_e32 v4, v85, v4
	v_add_f32_e32 v4, v86, v4
	v_add_f32_e32 v4, v87, v4
	v_cvt_pk_bf16_f32 v142, v82, v83
	v_cvt_pk_bf16_f32 v143, v84, v85
	s_add_i32 s98, s74, s85
	s_mov_b32 s99, m0
	s_mov_b32 m0, s98
	s_nop 0
	global_load_lds_dwordx4 v[188:189], off
	s_add_i32 s98, s87, s86
	s_mov_b32 m0, s98
	s_nop 0
	global_load_lds_dwordx4 v[186:187], off
	s_mov_b32 m0, s99
	ds_read_b64_tr_b16 v[178:179], v6 offset:28672
	ds_read_b64_tr_b16 v[180:181], v6 offset:29184
	s_waitcnt lgkmcnt(10)
	v_mfma_f32_32x32x16_bf16 v[66:81], v[150:153], v[130:133], v[66:81]
	v_add_f32_e32 v4, v88, v4
	v_add_f32_e32 v4, v89, v4
	v_add_f32_e32 v4, v90, v4
	v_add_f32_e32 v4, v91, v4
	v_cvt_pk_bf16_f32 v144, v86, v87
	v_cvt_pk_bf16_f32 v145, v88, v89
	ds_read_b64_tr_b16 v[162:163], v6 offset:25600
	ds_read_b64_tr_b16 v[164:165], v6 offset:26112
	s_waitcnt lgkmcnt(11)
	v_mfma_f32_32x32x16_bf16 v[98:113], v[170:173], v[126:129], v[98:113]
	v_add_f32_e32 v4, v92, v4
	v_add_f32_e32 v4, v93, v4
	v_add_f32_e32 v4, v94, v4
	v_add_f32_e32 v4, v95, v4
	v_cvt_pk_bf16_f32 v138, v90, v91
	v_cvt_pk_bf16_f32 v139, v92, v93
	ds_read_b64_tr_b16 v[150:151], v6 offset:29696
	ds_read_b64_tr_b16 v[152:153], v6 offset:30208
	s_waitcnt lgkmcnt(12)
	v_mfma_f32_32x32x16_bf16 v[66:81], v[146:149], v[126:129], v[66:81]
	v_add_f32_e32 v4, v96, v4
	v_add_f32_e32 v4, v97, v4
	v_add_f32_e32 v4, v50, v4
	v_add_f32_e32 v4, v51, v4
	v_cvt_pk_bf16_f32 v140, v94, v95
	v_cvt_pk_bf16_f32 v141, v96, v97
	ds_read_b64_tr_b16 v[146:147], v6 offset:26624
	ds_read_b64_tr_b16 v[148:149], v6 offset:27136
	s_waitcnt lgkmcnt(13)
	v_mfma_f32_32x32x16_bf16 v[98:113], v[166:169], v[118:121], v[98:113]
	v_add_f32_e32 v4, v52, v4
	v_add_f32_e32 v4, v53, v4
	v_add_f32_e32 v4, v54, v4
	v_add_f32_e32 v4, v55, v4
	v_cvt_pk_bf16_f32 v134, v50, v51
	v_cvt_pk_bf16_f32 v135, v52, v53
	ds_read_b64_tr_b16 v[12:13], v6 offset:30720
	ds_read_b64_tr_b16 v[14:15], v6 offset:31232
	s_waitcnt lgkmcnt(14)
	v_mfma_f32_32x32x16_bf16 v[66:81], v[154:157], v[118:121], v[66:81]
	v_add_f32_e32 v4, v56, v4
	v_add_f32_e32 v4, v57, v4
	v_add_f32_e32 v4, v58, v4
	v_add_f32_e32 v4, v59, v4
	v_cvt_pk_bf16_f32 v136, v54, v55
	v_cvt_pk_bf16_f32 v137, v56, v57
	ds_read_b64_tr_b16 v[8:9], v6 offset:27648
	ds_read_b64_tr_b16 v[10:11], v6 offset:28160
	s_waitcnt lgkmcnt(14)
	v_mfma_f32_32x32x16_bf16 v[98:113], v[174:177], v[114:117], v[98:113]
	v_add_f32_e32 v4, v60, v4
	v_add_f32_e32 v4, v61, v4
	v_add_f32_e32 v4, v62, v4
	v_add_f32_e32 v16, v63, v4
	v_cvt_pk_bf16_f32 v122, v58, v59
	v_cvt_pk_bf16_f32 v123, v60, v61
	ds_read_b64_tr_b16 v[4:5], v6 offset:31744
	ds_read_b64_tr_b16 v[6:7], v6 offset:32256
	v_mfma_f32_32x32x16_bf16 v[66:81], v[158:161], v[114:117], v[66:81]
	v_add_f32_e32 v16, v64, v16
	v_add_f32_e32 v16, v65, v16
	v_add_f32_e32 v16, 0, v16
	v_cvt_pk_bf16_f32 v124, v62, v63
	v_cvt_pk_bf16_f32 v125, v64, v65
	v_max_f32_e32 v17, v99, v99
	v_max_f32_e32 v50, v98, v98
	v_max_f32_e32 v17, v50, v17
	s_nop 3
	v_max3_f32 v50, v100, v101, v67
	v_max3_f32 v17, v17, v66, v68
	v_max3_f32 v17, v17, v69, v102
	v_max3_f32 v50, v50, v104, v105
	v_max3_f32 v17, v17, v103, v70
	v_max3_f32 v50, v50, v72, v73
	v_max3_f32 v17, v17, v71, v106
	v_max3_f32 v50, v50, v108, v109
	v_max3_f32 v17, v17, v107, v74
	v_max3_f32 v50, v50, v76, v77
	v_max3_f32 v17, v17, v75, v110
	v_max3_f32 v50, v50, v112, v113
	v_max3_f32 v17, v17, v111, v78
	v_max3_f32 v50, v50, v80, v81
	v_add_f32_e32 v233, v2, v16
	v_max3_f32 v2, v17, v79, v50
	v_mov_b32_e32 v16, v2
	s_nop 1
	v_permlane32_swap_b32_e32 v2, v16
	v_max_f32_e32 v16, v16, v16
	v_max_f32_e32 v2, v2, v2
	v_max_f32_e32 v2, v2, v16
	v_cmp_lt_f32_e32 vcc, s81, v2
	s_cmp_lg_u64 vcc, 0
	s_cselect_b64 s[70:71], -1, 0
	s_cbranch_vccnz .LBB0_1108

	.amdhsa_kernel _Z9hymba_fwd4Args
		.amdhsa_group_segment_fixed_size 0
		.amdhsa_private_segment_fixed_size 0
		.amdhsa_kernarg_size 408
		.amdhsa_user_sgpr_count 2
		.amdhsa_user_sgpr_dispatch_ptr 0
		.amdhsa_user_sgpr_queue_ptr 0
		.amdhsa_user_sgpr_kernarg_segment_ptr 1
		.amdhsa_user_sgpr_dispatch_id 0
		.amdhsa_user_sgpr_kernarg_preload_length 0
		.amdhsa_user_sgpr_kernarg_preload_offset 0
		.amdhsa_user_sgpr_private_segment_size 0
		.amdhsa_uses_dynamic_stack 0
		.amdhsa_enable_private_segment 0
		.amdhsa_system_sgpr_workgroup_id_x 1
		.amdhsa_system_sgpr_workgroup_id_y 0
		.amdhsa_system_sgpr_workgroup_id_z 0
		.amdhsa_system_sgpr_workgroup_info 0
		.amdhsa_system_vgpr_workitem_id 0
		.amdhsa_next_free_vgpr 255
		.amdhsa_next_free_sgpr 102
		.amdhsa_accum_offset 256
		.amdhsa_reserve_vcc 1
		.amdhsa_float_round_mode_32 0
		.amdhsa_float_round_mode_16_64 0
		.amdhsa_float_denorm_mode_32 3
		.amdhsa_float_denorm_mode_16_64 3
		.amdhsa_dx10_clamp 1
		.amdhsa_ieee_mode 1
		.amdhsa_fp16_overflow 0
		.amdhsa_tg_split 0
		.amdhsa_exception_fp_ieee_invalid_op 0
		.amdhsa_exception_fp_denorm_src 0
		.amdhsa_exception_fp_ieee_div_zero 0
		.amdhsa_exception_fp_ieee_overflow 0
		.amdhsa_exception_fp_ieee_underflow 0
		.amdhsa_exception_fp_ieee_inexact 0
		.amdhsa_exception_int_div_zero 0
	.end_amdhsa_kernel

amdhsa.kernels:
  - .agpr_count:     0
    .args:
      - .offset:         0
        .size:           152
        .value_kind:     by_value
      - .offset:         152
        .size:           4
        .value_kind:     hidden_block_count_x
      - .offset:         156
        .size:           4
        .value_kind:     hidden_block_count_y
      - .offset:         160
        .size:           4
        .value_kind:     hidden_block_count_z
      - .offset:         164
        .size:           2
        .value_kind:     hidden_group_size_x
      - .offset:         166
        .size:           2
        .value_kind:     hidden_group_size_y
      - .offset:         168
        .size:           2
        .value_kind:     hidden_group_size_z
      - .offset:         170
        .size:           2
        .value_kind:     hidden_remainder_x
      - .offset:         172
        .size:           2
        .value_kind:     hidden_remainder_y
      - .offset:         174
        .size:           2
        .value_kind:     hidden_remainder_z
      - .offset:         192
        .size:           8
        .value_kind:     hidden_global_offset_x
      - .offset:         200
        .size:           8
        .value_kind:     hidden_global_offset_y
      - .offset:         208
        .size:           8
        .value_kind:     hidden_global_offset_z
      - .offset:         216
        .size:           2
        .value_kind:     hidden_grid_dims
      - .offset:         272
        .size:           4
        .value_kind:     hidden_dynamic_lds_size
    .group_segment_fixed_size: 0
    .kernarg_segment_align: 8
    .kernarg_segment_size: 408
    .language:       OpenCL C
    .language_version:
      - 2
      - 0
    .max_flat_workgroup_size: 512
    .name:           _Z9hymba_fwd4Args
    .private_segment_fixed_size: 0
    .sgpr_count:     108
    .sgpr_spill_count: 4
    .symbol:         _Z9hymba_fwd4Args.kd
    .uniform_work_group_size: 1
    .uses_dynamic_stack: false
    .vgpr_count:     255
    .vgpr_spill_count: 0
    .wavefront_size: 64
